# stack + P6 EpiLN epilogue operands (row stats, cs/bc) staged into a spare LDS slice by header LDS-DMA, read with ds_read; epilogue vmcnt(0) drain removed
# baseline (speedup 1.0000x reference)
;     __host__ __device__ bool next(int i, Unit& u) const { const bool ok = so.next(i >> 1, u); u.part = i & 1; return ok; }
;     __host__ __device__ bool next(int i, Unit& u) const { return at((long)i * G + c, u); }
;     __host__ __device__ bool at(long L, Unit& u) const {
;         if (L >= nwg) return false;
;         int wgid = (int)L; { const int q = nwg / NXCD, r = nwg % NXCD, xcd = wgid % NXCD, off = wgid / NXCD; wgid = (xcd < r ? xcd * (q + 1) : r * (q + 1) + (xcd - r) * q) + off; }
;         const int nig = WGM * nN, gid = wgid / nig, fm = gid * WGM, gsz = (nM - fm) < WGM ? (nM - fm) : WGM;
;         u.pm = fm + ((wgid % nig) % gsz); u.pn = (wgid % nig) / gsz; u.part = 0; return true;
;     }
;     __device__ __forceinline__ void operator()(const f32x4 (&acc)[2][2][4][2], const Unit& u, int wr, int wc, int fr, int fq) const {
;         const int row0 = u.pm * BM + wr * 64 + fr; const int col0 = u.pn * BM + wc * 32 + 8 * fq; const int bcol0 = col0 + (u.pn >= skip_tile ? skip : 0);
;         f32x2 sv[2][4];
; #pragma unroll
;         for (int ai = 0; ai < 2; ++ai)
; #pragma unroll
;             for (int m = 0; m < 4; ++m) sv[ai][m] = *(const f32x2*)(stats + 2 * (size_t)(row0 + ai * HALF + m * 16));
;         f32x4 cv[2][2], bv[2][2];
; #pragma unroll
;         for (int bj = 0; bj < 2; ++bj)
; #pragma unroll
;             for (int n = 0; n < 2; ++n) { cv[bj][n] = *(const f32x4*)(cs + bcol0 + bj * HALF + 4 * n); bv[bj][n] = *(const f32x4*)(bc + bcol0 + bj * HALF + 4 * n); }
.LBB0_812:
	s_add_i32 s80, s80, 1
	s_and_b32 s4, s80, 1
	s_lshl_b32 s4, s4, 12
	s_add_i32 s4, s4, 0x20400
	v_mbcnt_lo_u32_b32 v130, -1, 0
	v_mbcnt_hi_u32_b32 v130, -1, v130
	v_lshlrev_b32_e32 v130, 4, v130
	v_add_u32_e32 v131, 0x400, v130
	s_lshl_b32 s5, s82, 11
	s_add_u32 s44, s46, s5
	s_addc_u32 s45, s47, 0
	s_mov_b32 m0, s4
	s_nop 0
	global_load_lds_dwordx4 v130, s[44:45]
	s_add_i32 m0, s4, 0x400
	s_nop 0
	global_load_lds_dwordx4 v131, s[44:45]
	s_lshl_b32 s5, s81, 10
	s_add_u32 s44, s18, s5
	s_addc_u32 s45, s19, 0
	s_add_i32 m0, s4, 0x800
	s_nop 0
	global_load_lds_dwordx4 v130, s[44:45]
	s_add_u32 s44, s22, s5
	s_addc_u32 s45, s23, 0
	s_add_i32 m0, s4, 0xc00
	s_nop 0
	global_load_lds_dwordx4 v130, s[44:45]
	s_mul_i32 s4, s80, s33
	s_mul_hi_u32 s5, s80, s56
	s_add_i32 s5, s5, s4
	s_mul_i32 s4, s80, s56
	s_add_u32 s44, s4, s2
	s_addc_u32 s45, s5, s27
	v_mov_b64_e32 v[2:3], 0xb00
	v_cmp_gt_i64_e32 vcc, s[44:45], v[184:185]
	v_cmp_lt_i64_e64 s[40:41], s[44:45], v[2:3]
	s_cbranch_vccnz .LBB0_814
	s_ashr_i32 s4, s44, 31
	s_lshr_b32 s4, s4, 29
	s_add_i32 s4, s44, s4
	s_ashr_i32 s5, s4, 3
	s_and_b32 s4, s4, -8
	s_sub_i32 s4, s44, s4
	s_cmp_lt_i32 s4, 0
	s_movk_i32 s38, 0x161
	s_cselect_b32 s38, s38, 0x160
	s_mul_i32 s4, s4, s38
	s_add_i32 s4, s4, s5
	s_mul_hi_i32 s5, s4, 0x2e8ba2e9
	s_lshr_b32 s38, s5, 31
	s_ashr_i32 s5, s5, 5
	s_add_i32 s5, s5, s38
	s_lshl_b32 s39, s5, 3
	s_sub_i32 s38, 0x80, s39
	s_min_i32 s42, s38, 8
	s_abs_i32 s38, s42
	v_cvt_f32_u32_e32 v2, s38
	s_sub_i32 s44, 0, s38
	s_mulk_i32 s5, 0xb0
	s_sub_i32 s4, s4, s5
	v_rcp_iflag_f32_e32 v2, v2
	s_abs_i32 s5, s4
	s_xor_b32 s43, s4, s42
	s_ashr_i32 s43, s43, 31
	v_mul_f32_e32 v2, 0x4f7ffffe, v2
	v_cvt_u32_f32_e32 v2, v2
	s_nop 0
	v_readfirstlane_b32 s45, v2
	s_mul_i32 s44, s44, s45
	s_mul_hi_u32 s44, s45, s44
	s_add_i32 s45, s45, s44
	s_mul_hi_u32 s44, s5, s45
	s_mul_i32 s45, s44, s38
	s_sub_i32 s5, s5, s45
	s_add_i32 s48, s44, 1
	s_sub_i32 s45, s5, s38
	s_cmp_ge_u32 s5, s38
	s_cselect_b32 s44, s48, s44
	s_cselect_b32 s5, s45, s5
	s_add_i32 s45, s44, 1
	s_cmp_ge_u32 s5, s38
	s_cselect_b32 s5, s45, s44
	s_xor_b32 s5, s5, s43
	s_sub_i32 s38, s5, s43
	s_mul_i32 s5, s38, s42
	s_sub_i32 s4, s4, s5
	s_add_i32 s42, s39, s4

; __device__ __forceinline__ unsigned cvt_pk_bf16(float lo, float hi) { unsigned r; asm volatile("v_cvt_pk_bf16_f32 %0, %1, %2" : "=v"(r) : "v"(lo), "v"(hi)); return r; }
; __device__ __forceinline__ void stats_mr(const f32x2 s, float& mu, float& r) { mu = s.x * (1.0f / 1024.0f); const float var = s.y * (1.0f / 1024.0f) - mu * mu; r = __builtin_amdgcn_rsqf(var + 1e-5f); }
;     __device__ __forceinline__ void operator()(const f32x4 (&acc)[2][2][4][2], const Unit& u, int wr, int wc, int fr, int fq) const {
;         const int row0 = u.pm * BM + wr * 64 + fr; const int col0 = u.pn * BM + wc * 32 + 8 * fq; const int bcol0 = col0 + (u.pn >= skip_tile ? skip : 0);
;         f32x2 sv[2][4];
; #pragma unroll
;         for (int ai = 0; ai < 2; ++ai)
; #pragma unroll
;             for (int m = 0; m < 4; ++m) sv[ai][m] = *(const f32x2*)(stats + 2 * (size_t)(row0 + ai * HALF + m * 16));
;         f32x4 cv[2][2], bv[2][2];
; #pragma unroll
;         for (int bj = 0; bj < 2; ++bj)
; #pragma unroll
;             for (int n = 0; n < 2; ++n) { cv[bj][n] = *(const f32x4*)(cs + bcol0 + bj * HALF + 4 * n); bv[bj][n] = *(const f32x4*)(bc + bcol0 + bj * HALF + 4 * n); }
; #pragma unroll
;         for (int ai = 0; ai < 2; ++ai)
; #pragma unroll
;             for (int m = 0; m < 4; ++m) { const int row = row0 + ai * HALF + m * 16; bf16_t* rowp = O + (size_t)row * ldc + col0;
;                 float mu, r; stats_mr(sv[ai][m], mu, r);
; #pragma unroll
;                 for (int bj = 0; bj < 2; ++bj) { const f32x4 v0 = (acc[ai][bj][m][0] - cv[bj][0] * mu) * r + bv[bj][0], v1 = (acc[ai][bj][m][1] - cv[bj][1] * mu) * r + bv[bj][1];
;                     u32x4 w; w.x = cvt_pk_bf16(v0[0], v0[1]); w.y = cvt_pk_bf16(v0[2], v0[3]); w.z = cvt_pk_bf16(v1[0], v1[1]); w.w = cvt_pk_bf16(v1[2], v1[3]);
;                     *(u32x4*)(rowp + bj * HALF) = w; } }
.LBB0_818:
	s_and_b32 s50, s80, 1
	s_lshl_b32 s50, s50, 12
	s_add_i32 s50, s50, 0x20400
	v_lshl_add_u32 v250, v1, 3, s50
	s_addk_i32 s50, 0x800
	v_lshl_add_u32 v251, v201, 2, s50
	v_lshl_add_u32 v178, s82, 8, v1
	v_ashrrev_i32_e32 v179, 31, v178
	v_lshl_or_b32 v188, s81, 8, v201
	v_lshl_add_u64 v[130:131], v[178:179], 3, s[46:47]
	v_ashrrev_i32_e32 v189, 31, v188
	v_or_b32_e32 v192, 16, v178
	ds_read_b64 v[204:205], v250
	v_lshlrev_b64 v[138:139], 2, v[188:189]
	v_ashrrev_i32_e32 v193, 31, v192
	v_lshl_add_u64 v[134:135], s[18:19], 0, v[138:139]
	v_lshl_add_u64 v[140:141], v[192:193], 3, s[46:47]
	ds_read_b128 v[154:157], v251
	ds_read_b128 v[146:149], v251 offset:16
	ds_read_b128 v[130:133], v251 offset:528
	s_nop 0
	ds_read_b128 v[134:137], v251 offset:512
	v_lshl_add_u64 v[138:139], s[22:23], 0, v[138:139]
	ds_read_b64 v[206:207], v250 offset:128
	ds_read_b128 v[158:161], v251 offset:1024
	ds_read_b128 v[150:153], v251 offset:1040
	ds_read_b128 v[142:145], v251 offset:1536
	s_nop 0
	ds_read_b128 v[138:141], v251 offset:1552
	v_or_b32_e32 v208, 32, v178
	v_mov_b64_e32 v[174:175], s[66:67]
	v_ashrrev_i32_e32 v209, 31, v208
	v_or_b32_e32 v198, 48, v178
	v_add_u32_e32 v194, 0x80, v178
	v_add_u32_e32 v190, 0x90, v178
	v_add_u32_e32 v186, 0xa0, v178
	v_add_u32_e32 v176, 0xb0, v178
	v_mad_i64_i32 v[196:197], s[24:25], v178, s69, v[174:175]
	v_lshl_add_u64 v[178:179], v[208:209], 3, s[46:47]
	ds_read_b64 v[210:211], v250 offset:256
	v_ashrrev_i32_e32 v199, 31, v198
	v_ashrrev_i32_e32 v195, 31, v194
	v_ashrrev_i32_e32 v191, 31, v190
	v_ashrrev_i32_e32 v187, 31, v186
	v_ashrrev_i32_e32 v177, 31, v176
	v_lshlrev_b64 v[178:179], 1, v[188:189]
	v_mad_i64_i32 v[188:189], s[24:25], v192, s69, v[174:175]
	v_lshl_add_u64 v[192:193], v[198:199], 3, s[46:47]
	v_lshl_add_u64 v[212:213], v[194:195], 3, s[46:47]
	v_lshl_add_u64 v[214:215], v[190:191], 3, s[46:47]
	v_lshl_add_u64 v[216:217], v[186:187], 3, s[46:47]
	v_lshl_add_u64 v[218:219], v[176:177], 3, s[46:47]
	v_lshl_add_u64 v[220:221], v[196:197], 0, v[178:179]
	v_lshl_add_u64 v[234:235], v[188:189], 0, v[178:179]
	ds_read_b64 v[236:237], v250 offset:384
	s_nop 0
	ds_read_b64 v[212:213], v250 offset:1024
	s_nop 0
	ds_read_b64 v[196:197], v250 offset:1152
	ds_read_b64 v[192:193], v250 offset:1280
	ds_read_b64 v[188:189], v250 offset:1408
	v_readlane_b32 s50, v255, 58
	s_andn2_b64 vcc, exec, s[40:41]
	v_readlane_b32 s51, v255, 59
	s_waitcnt lgkmcnt(0)
	v_pk_mul_f32 v[204:205], v[204:205], s[54:55] op_sel_hi:[1,0]
	s_nop 0
	v_fma_f32 v177, -v204, v204, v205
	v_pk_fma_f32 v[126:127], v[204:205], v[154:155], v[126:127] op_sel_hi:[0,1,1] neg_lo:[1,0,0] neg_hi:[1,0,0]
	v_pk_fma_f32 v[128:129], v[204:205], v[156:157], v[128:129] op_sel_hi:[0,1,1] neg_lo:[1,0,0] neg_hi:[1,0,0]
	v_pk_fma_f32 v[122:123], v[204:205], v[146:147], v[122:123] op_sel_hi:[0,1,1] neg_lo:[1,0,0] neg_hi:[1,0,0]
	v_pk_fma_f32 v[124:125], v[204:205], v[148:149], v[124:125] op_sel_hi:[0,1,1] neg_lo:[1,0,0] neg_hi:[1,0,0]
	v_pk_fma_f32 v[110:111], v[204:205], v[134:135], v[110:111] op_sel_hi:[0,1,1] neg_lo:[1,0,0] neg_hi:[1,0,0]
	v_pk_fma_f32 v[112:113], v[204:205], v[136:137], v[112:113] op_sel_hi:[0,1,1] neg_lo:[1,0,0] neg_hi:[1,0,0]
	v_pk_fma_f32 v[106:107], v[204:205], v[130:131], v[106:107] op_sel_hi:[0,1,1] neg_lo:[1,0,0] neg_hi:[1,0,0]
	v_pk_fma_f32 v[108:109], v[204:205], v[132:133], v[108:109] op_sel_hi:[0,1,1] neg_lo:[1,0,0] neg_hi:[1,0,0]
	v_pk_mul_f32 v[204:205], v[206:207], s[54:55] op_sel_hi:[1,0]
	v_add_f32_e32 v177, 0x3727c5ac, v177
	v_fma_f32 v187, -v204, v204, v205
	v_rsq_f32_e32 v206, v177
	v_add_f32_e32 v177, 0x3727c5ac, v187
	v_rsq_f32_e32 v214, v177
	v_pk_fma_f32 v[118:119], v[204:205], v[154:155], v[118:119] op_sel_hi:[0,1,1] neg_lo:[1,0,0] neg_hi:[1,0,0]
	v_pk_fma_f32 v[128:129], v[206:207], v[128:129], v[160:161] op_sel_hi:[0,1,1]
	v_pk_fma_f32 v[126:127], v[206:207], v[126:127], v[158:159] op_sel_hi:[0,1,1]
	v_pk_fma_f32 v[124:125], v[206:207], v[124:125], v[152:153] op_sel_hi:[0,1,1]
	v_pk_fma_f32 v[122:123], v[206:207], v[122:123], v[150:151] op_sel_hi:[0,1,1]
	v_pk_fma_f32 v[112:113], v[206:207], v[112:113], v[144:145] op_sel_hi:[0,1,1]
	v_pk_fma_f32 v[110:111], v[206:207], v[110:111], v[142:143] op_sel_hi:[0,1,1]
	v_pk_fma_f32 v[216:217], v[206:207], v[108:109], v[140:141] op_sel_hi:[0,1,1]
	v_pk_fma_f32 v[206:207], v[206:207], v[106:107], v[138:139] op_sel_hi:[0,1,1]
	v_cvt_pk_bf16_f32 v106, v126, v127
	v_cvt_pk_bf16_f32 v107, v128, v129
	v_cvt_pk_bf16_f32 v108, v122, v123
	v_cvt_pk_bf16_f32 v109, v124, v125
	v_pk_fma_f32 v[120:121], v[204:205], v[156:157], v[120:121] op_sel_hi:[0,1,1] neg_lo:[1,0,0] neg_hi:[1,0,0]
	v_pk_fma_f32 v[114:115], v[204:205], v[146:147], v[114:115] op_sel_hi:[0,1,1] neg_lo:[1,0,0] neg_hi:[1,0,0]
	global_store_dwordx4 v[220:221], v[106:109], off
	v_pk_fma_f32 v[116:117], v[204:205], v[148:149], v[116:117] op_sel_hi:[0,1,1] neg_lo:[1,0,0] neg_hi:[1,0,0]
	v_pk_fma_f32 v[120:121], v[214:215], v[120:121], v[160:161] op_sel_hi:[0,1,1]
	v_cvt_pk_bf16_f32 v106, v110, v111
	v_cvt_pk_bf16_f32 v107, v112, v113
	v_cvt_pk_bf16_f32 v108, v206, v207
	v_cvt_pk_bf16_f32 v109, v216, v217
	v_pk_fma_f32 v[118:119], v[214:215], v[118:119], v[158:159] op_sel_hi:[0,1,1]
	global_store_dwordx4 v[220:221], v[106:109], off offset:256
	v_pk_fma_f32 v[98:99], v[204:205], v[130:131], v[98:99] op_sel_hi:[0,1,1] neg_lo:[1,0,0] neg_hi:[1,0,0]
	v_pk_fma_f32 v[100:101], v[204:205], v[132:133], v[100:101] op_sel_hi:[0,1,1] neg_lo:[1,0,0] neg_hi:[1,0,0]
	v_pk_fma_f32 v[108:109], v[214:215], v[114:115], v[150:151] op_sel_hi:[0,1,1]
	v_cvt_pk_bf16_f32 v106, v118, v119
	v_cvt_pk_bf16_f32 v107, v120, v121
; __device__ __forceinline__ unsigned cvt_pk_bf16(float lo, float hi) { unsigned r; asm volatile("v_cvt_pk_bf16_f32 %0, %1, %2" : "=v"(r) : "v"(lo), "v"(hi)); return r; }
; __device__ __forceinline__ void stats_mr(const f32x2 s, float& mu, float& r) { mu = s.x * (1.0f / 1024.0f); const float var = s.y * (1.0f / 1024.0f) - mu * mu; r = __builtin_amdgcn_rsqf(var + 1e-5f); }
;     __device__ __forceinline__ void operator()(const f32x4 (&acc)[2][2][4][2], const Unit& u, int wr, int wc, int fr, int fq) const {
;     ...
;         for (int ai = 0; ai < 2; ++ai)
; #pragma unroll
;             for (int m = 0; m < 4; ++m) { const int row = row0 + ai * HALF + m * 16; bf16_t* rowp = O + (size_t)row * ldc + col0;
;                 float mu, r; stats_mr(sv[ai][m], mu, r);
; #pragma unroll
;                 for (int bj = 0; bj < 2; ++bj) { const f32x4 v0 = (acc[ai][bj][m][0] - cv[bj][0] * mu) * r + bv[bj][0], v1 = (acc[ai][bj][m][1] - cv[bj][1] * mu) * r + bv[bj][1];
;                     u32x4 w; w.x = cvt_pk_bf16(v0[0], v0[1]); w.y = cvt_pk_bf16(v0[2], v0[3]); w.z = cvt_pk_bf16(v1[0], v1[1]); w.w = cvt_pk_bf16(v1[2], v1[3]);
;                     *(u32x4*)(rowp + bj * HALF) = w; } }
	v_pk_fma_f32 v[116:117], v[214:215], v[116:117], v[152:153] op_sel_hi:[0,1,1]
	v_cvt_pk_bf16_f32 v108, v108, v109
	v_cvt_pk_bf16_f32 v109, v116, v117
	global_store_dwordx4 v[234:235], v[106:109], off
	v_pk_fma_f32 v[102:103], v[204:205], v[134:135], v[102:103] op_sel_hi:[0,1,1] neg_lo:[1,0,0] neg_hi:[1,0,0]
	v_pk_fma_f32 v[104:105], v[204:205], v[136:137], v[104:105] op_sel_hi:[0,1,1] neg_lo:[1,0,0] neg_hi:[1,0,0]
	v_pk_fma_f32 v[106:107], v[214:215], v[100:101], v[140:141] op_sel_hi:[0,1,1]
	v_pk_fma_f32 v[100:101], v[214:215], v[98:99], v[138:139] op_sel_hi:[0,1,1]
	v_pk_fma_f32 v[104:105], v[214:215], v[104:105], v[144:145] op_sel_hi:[0,1,1]
	v_pk_fma_f32 v[102:103], v[214:215], v[102:103], v[142:143] op_sel_hi:[0,1,1]
	v_cvt_pk_bf16_f32 v98, v102, v103
	v_cvt_pk_bf16_f32 v99, v104, v105
	v_cvt_pk_bf16_f32 v100, v100, v101
	v_cvt_pk_bf16_f32 v101, v106, v107
	global_store_dwordx4 v[234:235], v[98:101], off offset:256
	s_nop 1
	v_pk_mul_f32 v[100:101], v[210:211], s[54:55] op_sel_hi:[1,0]
	v_mad_i64_i32 v[98:99], s[24:25], v208, s69, v[174:175]
	v_fma_f32 v102, -v100, v100, v101
	v_add_f32_e32 v102, 0x3727c5ac, v102
	v_rsq_f32_e32 v102, v102
	v_pk_fma_f32 v[94:95], v[100:101], v[154:155], v[94:95] op_sel_hi:[0,1,1] neg_lo:[1,0,0] neg_hi:[1,0,0]
	v_pk_fma_f32 v[96:97], v[100:101], v[156:157], v[96:97] op_sel_hi:[0,1,1] neg_lo:[1,0,0] neg_hi:[1,0,0]
	v_pk_fma_f32 v[90:91], v[100:101], v[146:147], v[90:91] op_sel_hi:[0,1,1] neg_lo:[1,0,0] neg_hi:[1,0,0]
	v_pk_fma_f32 v[92:93], v[100:101], v[148:149], v[92:93] op_sel_hi:[0,1,1] neg_lo:[1,0,0] neg_hi:[1,0,0]
	v_lshl_add_u64 v[98:99], v[98:99], 0, v[178:179]
	v_pk_fma_f32 v[96:97], v[102:103], v[96:97], v[160:161] op_sel_hi:[0,1,1]
	v_pk_fma_f32 v[94:95], v[102:103], v[94:95], v[158:159] op_sel_hi:[0,1,1]
	v_pk_fma_f32 v[104:105], v[102:103], v[92:93], v[152:153] op_sel_hi:[0,1,1]
	v_pk_fma_f32 v[92:93], v[102:103], v[90:91], v[150:151] op_sel_hi:[0,1,1]
	v_cvt_pk_bf16_f32 v90, v94, v95
	v_cvt_pk_bf16_f32 v91, v96, v97
	v_pk_fma_f32 v[82:83], v[100:101], v[130:131], v[82:83] op_sel_hi:[0,1,1] neg_lo:[1,0,0] neg_hi:[1,0,0]
	v_pk_fma_f32 v[84:85], v[100:101], v[132:133], v[84:85] op_sel_hi:[0,1,1] neg_lo:[1,0,0] neg_hi:[1,0,0]
	v_cvt_pk_bf16_f32 v92, v92, v93
	v_cvt_pk_bf16_f32 v93, v104, v105
	global_store_dwordx4 v[98:99], v[90:93], off
	v_pk_fma_f32 v[86:87], v[100:101], v[134:135], v[86:87] op_sel_hi:[0,1,1] neg_lo:[1,0,0] neg_hi:[1,0,0]
	v_pk_fma_f32 v[88:89], v[100:101], v[136:137], v[88:89] op_sel_hi:[0,1,1] neg_lo:[1,0,0] neg_hi:[1,0,0]
	v_pk_fma_f32 v[90:91], v[102:103], v[84:85], v[140:141] op_sel_hi:[0,1,1]
	v_pk_fma_f32 v[84:85], v[102:103], v[82:83], v[138:139] op_sel_hi:[0,1,1]
	v_pk_fma_f32 v[88:89], v[102:103], v[88:89], v[144:145] op_sel_hi:[0,1,1]
	v_pk_fma_f32 v[86:87], v[102:103], v[86:87], v[142:143] op_sel_hi:[0,1,1]
	v_cvt_pk_bf16_f32 v82, v86, v87
	v_cvt_pk_bf16_f32 v83, v88, v89
	v_cvt_pk_bf16_f32 v84, v84, v85
	v_cvt_pk_bf16_f32 v85, v90, v91
	global_store_dwordx4 v[98:99], v[82:85], off offset:256
	s_nop 1
	v_pk_mul_f32 v[84:85], v[236:237], s[54:55] op_sel_hi:[1,0]
	v_mad_i64_i32 v[82:83], s[24:25], v198, s69, v[174:175]
	v_fma_f32 v86, -v84, v84, v85
	v_add_f32_e32 v86, 0x3727c5ac, v86
	v_rsq_f32_e32 v86, v86
	v_pk_fma_f32 v[78:79], v[84:85], v[154:155], v[78:79] op_sel_hi:[0,1,1] neg_lo:[1,0,0] neg_hi:[1,0,0]
	v_pk_fma_f32 v[80:81], v[84:85], v[156:157], v[80:81] op_sel_hi:[0,1,1] neg_lo:[1,0,0] neg_hi:[1,0,0]
	v_pk_fma_f32 v[74:75], v[84:85], v[146:147], v[74:75] op_sel_hi:[0,1,1] neg_lo:[1,0,0] neg_hi:[1,0,0]
	v_pk_fma_f32 v[76:77], v[84:85], v[148:149], v[76:77] op_sel_hi:[0,1,1] neg_lo:[1,0,0] neg_hi:[1,0,0]
	v_lshl_add_u64 v[82:83], v[82:83], 0, v[178:179]
	v_pk_fma_f32 v[80:81], v[80:81], v[86:87], v[160:161] op_sel_hi:[1,0,1]
	v_pk_fma_f32 v[78:79], v[78:79], v[86:87], v[158:159] op_sel_hi:[1,0,1]
	v_pk_fma_f32 v[88:89], v[86:87], v[76:77], v[152:153] op_sel_hi:[0,1,1]
	v_pk_fma_f32 v[76:77], v[86:87], v[74:75], v[150:151] op_sel_hi:[0,1,1]
	v_cvt_pk_bf16_f32 v74, v78, v79
	v_cvt_pk_bf16_f32 v75, v80, v81
	v_pk_fma_f32 v[66:67], v[84:85], v[130:131], v[66:67] op_sel_hi:[0,1,1] neg_lo:[1,0,0] neg_hi:[1,0,0]
	v_pk_fma_f32 v[68:69], v[84:85], v[132:133], v[68:69] op_sel_hi:[0,1,1] neg_lo:[1,0,0] neg_hi:[1,0,0]
	v_cvt_pk_bf16_f32 v76, v76, v77
	v_cvt_pk_bf16_f32 v77, v88, v89
	global_store_dwordx4 v[82:83], v[74:77], off
	v_pk_fma_f32 v[70:71], v[84:85], v[134:135], v[70:71] op_sel_hi:[0,1,1] neg_lo:[1,0,0] neg_hi:[1,0,0]
	v_pk_fma_f32 v[72:73], v[84:85], v[136:137], v[72:73] op_sel_hi:[0,1,1] neg_lo:[1,0,0] neg_hi:[1,0,0]
	v_pk_fma_f32 v[74:75], v[86:87], v[68:69], v[140:141] op_sel_hi:[0,1,1]
	v_pk_fma_f32 v[68:69], v[86:87], v[66:67], v[138:139] op_sel_hi:[0,1,1]
	v_pk_fma_f32 v[72:73], v[86:87], v[72:73], v[144:145] op_sel_hi:[0,1,1]
	v_pk_fma_f32 v[70:71], v[86:87], v[70:71], v[142:143] op_sel_hi:[0,1,1]
	v_cvt_pk_bf16_f32 v66, v70, v71
	v_cvt_pk_bf16_f32 v67, v72, v73
	v_cvt_pk_bf16_f32 v68, v68, v69
	v_cvt_pk_bf16_f32 v69, v74, v75
	global_store_dwordx4 v[82:83], v[66:69], off offset:256
	s_nop 1
	v_pk_mul_f32 v[68:69], v[212:213], s[54:55] op_sel_hi:[1,0]
	v_mad_i64_i32 v[66:67], s[24:25], v194, s69, v[174:175]
	v_fma_f32 v70, -v68, v68, v69
	v_add_f32_e32 v70, 0x3727c5ac, v70
	v_rsq_f32_e32 v70, v70
	v_pk_fma_f32 v[62:63], v[68:69], v[154:155], v[62:63] op_sel_hi:[0,1,1] neg_lo:[1,0,0] neg_hi:[1,0,0]
	v_pk_fma_f32 v[64:65], v[68:69], v[156:157], v[64:65] op_sel_hi:[0,1,1] neg_lo:[1,0,0] neg_hi:[1,0,0]
	v_pk_fma_f32 v[58:59], v[68:69], v[146:147], v[58:59] op_sel_hi:[0,1,1] neg_lo:[1,0,0] neg_hi:[1,0,0]
; __device__ __forceinline__ unsigned cvt_pk_bf16(float lo, float hi) { unsigned r; asm volatile("v_cvt_pk_bf16_f32 %0, %1, %2" : "=v"(r) : "v"(lo), "v"(hi)); return r; }
; __device__ __forceinline__ void stats_mr(const f32x2 s, float& mu, float& r) { mu = s.x * (1.0f / 1024.0f); const float var = s.y * (1.0f / 1024.0f) - mu * mu; r = __builtin_amdgcn_rsqf(var + 1e-5f); }
;     __device__ __forceinline__ void operator()(const f32x4 (&acc)[2][2][4][2], const Unit& u, int wr, int wc, int fr, int fq) const {
;     ...
;         for (int ai = 0; ai < 2; ++ai)
; #pragma unroll
;             for (int m = 0; m < 4; ++m) { const int row = row0 + ai * HALF + m * 16; bf16_t* rowp = O + (size_t)row * ldc + col0;
;                 float mu, r; stats_mr(sv[ai][m], mu, r);
; #pragma unroll
;                 for (int bj = 0; bj < 2; ++bj) { const f32x4 v0 = (acc[ai][bj][m][0] - cv[bj][0] * mu) * r + bv[bj][0], v1 = (acc[ai][bj][m][1] - cv[bj][1] * mu) * r + bv[bj][1];
;                     u32x4 w; w.x = cvt_pk_bf16(v0[0], v0[1]); w.y = cvt_pk_bf16(v0[2], v0[3]); w.z = cvt_pk_bf16(v1[0], v1[1]); w.w = cvt_pk_bf16(v1[2], v1[3]);
;                     *(u32x4*)(rowp + bj * HALF) = w; } }
	v_pk_fma_f32 v[60:61], v[68:69], v[148:149], v[60:61] op_sel_hi:[0,1,1] neg_lo:[1,0,0] neg_hi:[1,0,0]
	v_lshl_add_u64 v[66:67], v[66:67], 0, v[178:179]
	v_pk_fma_f32 v[64:65], v[64:65], v[70:71], v[160:161] op_sel_hi:[1,0,1]
	v_pk_fma_f32 v[62:63], v[62:63], v[70:71], v[158:159] op_sel_hi:[1,0,1]
	v_pk_fma_f32 v[72:73], v[70:71], v[60:61], v[152:153] op_sel_hi:[0,1,1]
	v_pk_fma_f32 v[60:61], v[70:71], v[58:59], v[150:151] op_sel_hi:[0,1,1]
	v_cvt_pk_bf16_f32 v58, v62, v63
	v_cvt_pk_bf16_f32 v59, v64, v65
	v_pk_fma_f32 v[50:51], v[68:69], v[130:131], v[50:51] op_sel_hi:[0,1,1] neg_lo:[1,0,0] neg_hi:[1,0,0]
	v_pk_fma_f32 v[52:53], v[68:69], v[132:133], v[52:53] op_sel_hi:[0,1,1] neg_lo:[1,0,0] neg_hi:[1,0,0]
	v_cvt_pk_bf16_f32 v60, v60, v61
	v_cvt_pk_bf16_f32 v61, v72, v73
	global_store_dwordx4 v[66:67], v[58:61], off
	v_pk_fma_f32 v[54:55], v[68:69], v[134:135], v[54:55] op_sel_hi:[0,1,1] neg_lo:[1,0,0] neg_hi:[1,0,0]
	v_pk_fma_f32 v[56:57], v[68:69], v[136:137], v[56:57] op_sel_hi:[0,1,1] neg_lo:[1,0,0] neg_hi:[1,0,0]
	v_pk_fma_f32 v[58:59], v[70:71], v[52:53], v[140:141] op_sel_hi:[0,1,1]
	v_pk_fma_f32 v[52:53], v[70:71], v[50:51], v[138:139] op_sel_hi:[0,1,1]
	v_pk_fma_f32 v[56:57], v[70:71], v[56:57], v[144:145] op_sel_hi:[0,1,1]
	v_pk_fma_f32 v[54:55], v[70:71], v[54:55], v[142:143] op_sel_hi:[0,1,1]
	v_cvt_pk_bf16_f32 v50, v54, v55
	v_cvt_pk_bf16_f32 v51, v56, v57
	v_cvt_pk_bf16_f32 v52, v52, v53
	v_cvt_pk_bf16_f32 v53, v58, v59
	global_store_dwordx4 v[66:67], v[50:53], off offset:256
	v_xor_b32_e32 v57, 0x80000000, v157
	v_xor_b32_e32 v56, 0x80000000, v156
	v_pk_mul_f32 v[52:53], v[196:197], s[54:55] op_sel_hi:[1,0]
	v_mad_i64_i32 v[50:51], s[24:25], v190, s69, v[174:175]
	v_fma_f32 v54, -v52, v52, v53
	v_add_f32_e32 v54, 0x3727c5ac, v54
	v_rsq_f32_e32 v54, v54
	v_pk_fma_f32 v[46:47], v[154:155], v[52:53], v[46:47] op_sel_hi:[1,0,1] neg_lo:[1,0,0] neg_hi:[1,0,0]
	v_pk_fma_f32 v[48:49], v[56:57], v[52:53], v[48:49] op_sel_hi:[1,0,1]
	v_pk_fma_f32 v[42:43], v[52:53], v[146:147], v[42:43] op_sel_hi:[0,1,1] neg_lo:[1,0,0] neg_hi:[1,0,0]
	v_pk_fma_f32 v[44:45], v[52:53], v[148:149], v[44:45] op_sel_hi:[0,1,1] neg_lo:[1,0,0] neg_hi:[1,0,0]
	v_lshl_add_u64 v[50:51], v[50:51], 0, v[178:179]
	v_pk_fma_f32 v[48:49], v[48:49], v[54:55], v[160:161] op_sel_hi:[1,0,1]
	v_pk_fma_f32 v[46:47], v[46:47], v[54:55], v[158:159] op_sel_hi:[1,0,1]
	v_pk_fma_f32 v[58:59], v[44:45], v[54:55], v[152:153] op_sel_hi:[1,0,1]
	v_pk_fma_f32 v[44:45], v[42:43], v[54:55], v[150:151] op_sel_hi:[1,0,1]
	v_cvt_pk_bf16_f32 v42, v46, v47
	v_cvt_pk_bf16_f32 v43, v48, v49
	v_pk_fma_f32 v[34:35], v[52:53], v[130:131], v[34:35] op_sel_hi:[0,1,1] neg_lo:[1,0,0] neg_hi:[1,0,0]
	v_pk_fma_f32 v[36:37], v[52:53], v[132:133], v[36:37] op_sel_hi:[0,1,1] neg_lo:[1,0,0] neg_hi:[1,0,0]
	v_cvt_pk_bf16_f32 v44, v44, v45
	v_cvt_pk_bf16_f32 v45, v58, v59
	global_store_dwordx4 v[50:51], v[42:45], off
	v_pk_fma_f32 v[38:39], v[52:53], v[134:135], v[38:39] op_sel_hi:[0,1,1] neg_lo:[1,0,0] neg_hi:[1,0,0]
	v_pk_fma_f32 v[40:41], v[52:53], v[136:137], v[40:41] op_sel_hi:[0,1,1] neg_lo:[1,0,0] neg_hi:[1,0,0]
	v_pk_fma_f32 v[42:43], v[54:55], v[36:37], v[140:141] op_sel_hi:[0,1,1]
	v_pk_fma_f32 v[36:37], v[54:55], v[34:35], v[138:139] op_sel_hi:[0,1,1]
	v_pk_fma_f32 v[40:41], v[54:55], v[40:41], v[144:145] op_sel_hi:[0,1,1]
	v_pk_fma_f32 v[38:39], v[54:55], v[38:39], v[142:143] op_sel_hi:[0,1,1]
	v_cvt_pk_bf16_f32 v34, v38, v39
	v_cvt_pk_bf16_f32 v35, v40, v41
	v_cvt_pk_bf16_f32 v36, v36, v37
	v_cvt_pk_bf16_f32 v37, v42, v43
	global_store_dwordx4 v[50:51], v[34:37], off offset:256
	s_nop 1
	v_pk_mul_f32 v[36:37], v[192:193], s[54:55] op_sel_hi:[1,0]
	v_mad_i64_i32 v[34:35], s[24:25], v186, s69, v[174:175]
	v_fma_f32 v38, -v36, v36, v37
	v_add_f32_e32 v38, 0x3727c5ac, v38
	v_rsq_f32_e32 v38, v38
	v_pk_fma_f32 v[30:31], v[154:155], v[36:37], v[30:31] op_sel_hi:[1,0,1] neg_lo:[1,0,0] neg_hi:[1,0,0]
; __device__ __forceinline__ unsigned cvt_pk_bf16(float lo, float hi) { unsigned r; asm volatile("v_cvt_pk_bf16_f32 %0, %1, %2" : "=v"(r) : "v"(lo), "v"(hi)); return r; }
; __device__ __forceinline__ void stats_mr(const f32x2 s, float& mu, float& r) { mu = s.x * (1.0f / 1024.0f); const float var = s.y * (1.0f / 1024.0f) - mu * mu; r = __builtin_amdgcn_rsqf(var + 1e-5f); }
; template <class Epi, class Sched, bool ALIGN_EPI = false, bool SP2 = false>
; __device__ __forceinline__ void gemm_phase(PG8_LAS unsigned char* lds, const Gemm g, const Sched& S, const Epi& E) {
;     ...
;         if (!has_next) break;
;     __device__ __forceinline__ void operator()(const f32x4 (&acc)[2][2][4][2], const Unit& u, int wr, int wc, int fr, int fq) const {
;     ...
;         for (int ai = 0; ai < 2; ++ai)
; #pragma unroll
;             for (int m = 0; m < 4; ++m) { const int row = row0 + ai * HALF + m * 16; bf16_t* rowp = O + (size_t)row * ldc + col0;
;                 float mu, r; stats_mr(sv[ai][m], mu, r);
; #pragma unroll
;                 for (int bj = 0; bj < 2; ++bj) { const f32x4 v0 = (acc[ai][bj][m][0] - cv[bj][0] * mu) * r + bv[bj][0], v1 = (acc[ai][bj][m][1] - cv[bj][1] * mu) * r + bv[bj][1];
;                     u32x4 w; w.x = cvt_pk_bf16(v0[0], v0[1]); w.y = cvt_pk_bf16(v0[2], v0[3]); w.z = cvt_pk_bf16(v1[0], v1[1]); w.w = cvt_pk_bf16(v1[2], v1[3]);
;                     *(u32x4*)(rowp + bj * HALF) = w; } }
	v_pk_fma_f32 v[32:33], v[56:57], v[36:37], v[32:33] op_sel_hi:[1,0,1]
	v_pk_fma_f32 v[26:27], v[36:37], v[146:147], v[26:27] op_sel_hi:[0,1,1] neg_lo:[1,0,0] neg_hi:[1,0,0]
	v_pk_fma_f32 v[28:29], v[36:37], v[148:149], v[28:29] op_sel_hi:[0,1,1] neg_lo:[1,0,0] neg_hi:[1,0,0]
	v_lshl_add_u64 v[34:35], v[34:35], 0, v[178:179]
	v_pk_fma_f32 v[32:33], v[32:33], v[38:39], v[160:161] op_sel_hi:[1,0,1]
	v_pk_fma_f32 v[30:31], v[30:31], v[38:39], v[158:159] op_sel_hi:[1,0,1]
	v_pk_fma_f32 v[40:41], v[28:29], v[38:39], v[152:153] op_sel_hi:[1,0,1]
	v_pk_fma_f32 v[28:29], v[26:27], v[38:39], v[150:151] op_sel_hi:[1,0,1]
	v_cvt_pk_bf16_f32 v26, v30, v31
	v_cvt_pk_bf16_f32 v27, v32, v33
	v_pk_fma_f32 v[18:19], v[36:37], v[130:131], v[18:19] op_sel_hi:[0,1,1] neg_lo:[1,0,0] neg_hi:[1,0,0]
	v_pk_fma_f32 v[20:21], v[36:37], v[132:133], v[20:21] op_sel_hi:[0,1,1] neg_lo:[1,0,0] neg_hi:[1,0,0]
	v_cvt_pk_bf16_f32 v28, v28, v29
	v_cvt_pk_bf16_f32 v29, v40, v41
	global_store_dwordx4 v[34:35], v[26:29], off
	v_pk_fma_f32 v[22:23], v[36:37], v[134:135], v[22:23] op_sel_hi:[0,1,1] neg_lo:[1,0,0] neg_hi:[1,0,0]
	v_pk_fma_f32 v[24:25], v[36:37], v[136:137], v[24:25] op_sel_hi:[0,1,1] neg_lo:[1,0,0] neg_hi:[1,0,0]
	v_pk_fma_f32 v[26:27], v[38:39], v[20:21], v[140:141] op_sel_hi:[0,1,1]
	v_pk_fma_f32 v[20:21], v[38:39], v[18:19], v[138:139] op_sel_hi:[0,1,1]
	v_pk_fma_f32 v[24:25], v[38:39], v[24:25], v[144:145] op_sel_hi:[0,1,1]
	v_pk_fma_f32 v[22:23], v[38:39], v[22:23], v[142:143] op_sel_hi:[0,1,1]
	v_cvt_pk_bf16_f32 v18, v22, v23
	v_cvt_pk_bf16_f32 v19, v24, v25
	v_cvt_pk_bf16_f32 v20, v20, v21
	v_cvt_pk_bf16_f32 v21, v26, v27
	global_store_dwordx4 v[34:35], v[18:21], off offset:256
	v_xor_b32_e32 v25, 0x80000000, v149
	v_xor_b32_e32 v24, 0x80000000, v148
	v_pk_mul_f32 v[20:21], v[188:189], s[54:55] op_sel_hi:[1,0]
	v_mad_i64_i32 v[18:19], s[24:25], v176, s69, v[174:175]
	v_fma_f32 v22, -v20, v20, v21
	v_add_f32_e32 v22, 0x3727c5ac, v22
	v_rsq_f32_e32 v22, v22
	v_pk_fma_f32 v[14:15], v[154:155], v[20:21], v[14:15] op_sel_hi:[1,0,1] neg_lo:[1,0,0] neg_hi:[1,0,0]
	v_pk_fma_f32 v[16:17], v[56:57], v[20:21], v[16:17] op_sel_hi:[1,0,1]
	v_pk_fma_f32 v[10:11], v[146:147], v[20:21], v[10:11] op_sel_hi:[1,0,1] neg_lo:[1,0,0] neg_hi:[1,0,0]
	v_pk_fma_f32 v[12:13], v[24:25], v[20:21], v[12:13] op_sel_hi:[1,0,1]
	v_lshl_add_u64 v[18:19], v[18:19], 0, v[178:179]
	v_pk_fma_f32 v[16:17], v[16:17], v[22:23], v[160:161] op_sel_hi:[1,0,1]
	v_pk_fma_f32 v[14:15], v[14:15], v[22:23], v[158:159] op_sel_hi:[1,0,1]
	v_pk_fma_f32 v[24:25], v[12:13], v[22:23], v[152:153] op_sel_hi:[1,0,1]
	v_pk_fma_f32 v[12:13], v[10:11], v[22:23], v[150:151] op_sel_hi:[1,0,1]
	v_cvt_pk_bf16_f32 v10, v14, v15
	v_cvt_pk_bf16_f32 v11, v16, v17
	v_pk_fma_f32 v[2:3], v[20:21], v[130:131], v[2:3] op_sel_hi:[0,1,1] neg_lo:[1,0,0] neg_hi:[1,0,0]
	v_pk_fma_f32 v[4:5], v[20:21], v[132:133], v[4:5] op_sel_hi:[0,1,1] neg_lo:[1,0,0] neg_hi:[1,0,0]
	v_cvt_pk_bf16_f32 v12, v12, v13
	v_cvt_pk_bf16_f32 v13, v24, v25
	global_store_dwordx4 v[18:19], v[10:13], off
	v_pk_fma_f32 v[6:7], v[20:21], v[134:135], v[6:7] op_sel_hi:[0,1,1] neg_lo:[1,0,0] neg_hi:[1,0,0]
	v_pk_fma_f32 v[8:9], v[20:21], v[136:137], v[8:9] op_sel_hi:[0,1,1] neg_lo:[1,0,0] neg_hi:[1,0,0]
	v_pk_fma_f32 v[10:11], v[22:23], v[4:5], v[140:141] op_sel_hi:[0,1,1]
	v_pk_fma_f32 v[4:5], v[22:23], v[2:3], v[138:139] op_sel_hi:[0,1,1]
	s_mov_b64 s[24:25], -1
	v_pk_fma_f32 v[8:9], v[8:9], v[22:23], v[144:145] op_sel_hi:[1,0,1]
	v_pk_fma_f32 v[6:7], v[6:7], v[22:23], v[142:143] op_sel_hi:[1,0,1]
	s_nop 0
	v_cvt_pk_bf16_f32 v2, v6, v7
	v_cvt_pk_bf16_f32 v3, v8, v9
	v_cvt_pk_bf16_f32 v4, v4, v5
	v_cvt_pk_bf16_f32 v5, v10, v11
	global_store_dwordx4 v[18:19], v[2:5], off offset:256
	s_cbranch_vccnz .LBB0_811
	s_andn2_b64 vcc, exec, s[0:1]
	s_cbranch_vccnz .LBB0_810
	s_barrier
	s_branch .LBB0_810
